# phase_stat row loop software-pipelined (next row's loads issued before reducing the current row; vmcnt(1) leaves the rs store in flight)
# speedup vs baseline: 1.0130x; 1.0130x over previous
; __device__ __forceinline__ float wave_sum(float v) {
; #pragma unroll
;   for (int o = 32; o >= 1; o >>= 1) v += __shfl_xor(v, o);
;   return v;
; __device__ void phase_stat(const KP& p) {
;   int tid_ = threadIdx.x; asm volatile("" : "+v"(tid_));
;   const int lane = tid_ & 63, w = tid_ >> 6;
;   const bfr* hb = (const bfr*)(p.ws + OFF_HB);
;   float* rs = (float*)(p.ws + OFF_RS);
;   for (int row = p.bid * 8 + w; row < T_ROWS; row += p.nblk * 8) {
;     float ss = 0.f;
; #pragma unroll
;     for (int i = 0; i < 2; ++i) {
;       u32x4 v = *(const u32x4*)(hb + (size_t)row * DM + lane * 8 + 512 * i);
.LBB0_27:
	v_readlane_b32 s0, v255, 51
	v_readlane_b32 s1, v255, 52
	s_and_b64 vcc, exec, s[0:1]
	s_cbranch_vccz .LBB0_34
	s_waitcnt vmcnt(0)
	v_mov_b32_e32 v3, v156
	v_readlane_b32 s0, v255, 42
	s_lshl_b32 s0, s0, 3
	v_ashrrev_i32_e32 v2, 6, v3
	v_add_u32_e32 v0, s0, v2
	s_mov_b32 s1, 0x8400
	v_cmp_gt_i32_e32 vcc, s1, v0
	s_and_saveexec_b64 s[36:37], vcc
	s_cbranch_execz .LBB0_33
	v_and_b32_e32 v12, 63, v3
	v_and_b32_e32 v3, 64, v164
	v_add_u32_e32 v3, 64, v3
	v_xor_b32_e32 v4, 32, v164
	v_cmp_lt_i32_e32 vcc, v4, v3
	v_readlane_b32 s2, v255, 43
	v_readlane_b32 s3, v255, 44
	v_cndmask_b32_e32 v4, v164, v4, vcc
	v_lshlrev_b32_e32 v6, 2, v4
	v_xor_b32_e32 v4, 16, v164
	v_cmp_lt_i32_e32 vcc, v4, v3
	s_lshl_b32 s38, s2, 3
	s_ashr_i32 s1, s0, 31
	v_cndmask_b32_e32 v4, v164, v4, vcc
	v_lshlrev_b32_e32 v7, 2, v4
	v_xor_b32_e32 v4, 8, v164
	v_cmp_lt_i32_e32 vcc, v4, v3
	v_readlane_b32 s2, v255, 45
	v_readlane_b32 s3, v255, 46
	v_cndmask_b32_e32 v4, v164, v4, vcc
	s_waitcnt lgkmcnt(0)
	v_lshlrev_b32_e32 v8, 2, v4
	v_xor_b32_e32 v4, 4, v164
	v_cmp_lt_i32_e32 vcc, v4, v3
	s_ashr_i32 s39, s38, 31
	s_lshl_b64 s[40:41], s[38:39], 2
	v_cndmask_b32_e32 v4, v164, v4, vcc
	v_lshlrev_b32_e32 v9, 2, v4
	v_xor_b32_e32 v4, 2, v164
	v_cmp_lt_i32_e32 vcc, v4, v3
	s_lshl_b64 s[42:43], s[38:39], 11
	s_mov_b64 s[44:45], 0
	v_cndmask_b32_e32 v4, v164, v4, vcc
	v_lshlrev_b32_e32 v10, 2, v4
	v_xor_b32_e32 v4, 1, v164
	v_cmp_lt_i32_e32 vcc, v4, v3
	s_nop 1
	v_cndmask_b32_e32 v3, v164, v4, vcc
	v_lshlrev_b32_e32 v11, 2, v3
	v_ashrrev_i32_e32 v3, 31, v2
	v_lshl_add_u64 v[4:5], v[2:3], 0, s[0:1]
	v_lshl_add_u64 v[2:3], v[4:5], 2, s[2:3]
	v_lshlrev_b64 v[4:5], 11, v[4:5]
	s_mov_b64 s[0:1], 0x4200000
	v_lshl_or_b32 v4, v12, 4, v4
	v_lshl_add_u64 v[2:3], v[2:3], 0, s[0:1]
	v_lshl_add_u64 v[4:5], s[2:3], 0, v[4:5]
	s_mov_b64 s[0:1], 0x400
	v_cmp_eq_u32_e32 vcc, 0, v12
	v_lshl_add_u64 v[4:5], v[4:5], 0, s[0:1]
	global_load_dwordx4 v[12:15], v[4:5], off offset:-1024
	global_load_dwordx4 v[16:19], v[4:5], off
	global_load_dword v46, v[4:5], off
	s_branch .LBB0_31

; __device__ void phase_stat(const KP& p) {
;     ...
;   for (int row = p.bid * 8 + w; row < T_ROWS; row += p.nblk * 8) {
;     float ss = 0.f;
; #pragma unroll
;     for (int i = 0; i < 2; ++i) {
;       u32x4 v = *(const u32x4*)(hb + (size_t)row * DM + lane * 8 + 512 * i);
; #pragma unroll
;       for (int e = 0; e < 4; ++e) {
;         float a = __uint_as_float(v[e] << 16), b = __uint_as_float(v[e] & 0xffff0000u);
;         ss += a * a + b * b;
;       }
;     }
;     ss = wave_sum(ss);
;     if (lane == 0) rs[row] = rsqrtf(ss * (1.f / DM) + EPSF);
;   }
.LBB0_31:
	s_waitcnt lgkmcnt(0)
	s_waitcnt vmcnt(1)
	v_mov_b32_e32 v36, v12
	v_mov_b32_e32 v37, v13
	v_mov_b32_e32 v38, v14
	v_mov_b32_e32 v39, v15
	v_mov_b32_e32 v40, v16
	v_mov_b32_e32 v41, v17
	v_mov_b32_e32 v42, v18
	v_mov_b32_e32 v43, v19
	v_lshl_add_u64 v[44:45], v[4:5], 0, s[42:43]
	global_load_dwordx4 v[12:15], v[44:45], off offset:-1024
	global_load_dwordx4 v[16:19], v[44:45], off
	v_lshlrev_b32_e32 v20, 16, v36
	v_and_b32_e32 v36, 0xffff0000, v36
	v_lshlrev_b32_e32 v21, 16, v37
	v_and_b32_e32 v37, 0xffff0000, v37
	v_lshlrev_b32_e32 v22, 16, v38
	v_and_b32_e32 v38, 0xffff0000, v38
	v_mul_f32_e32 v36, v36, v36
	v_mul_f32_e32 v37, v37, v37
	v_lshlrev_b32_e32 v23, 16, v39
	v_and_b32_e32 v39, 0xffff0000, v39
	v_mul_f32_e32 v38, v38, v38
	v_fmac_f32_e32 v36, v20, v20
	v_fmac_f32_e32 v37, v21, v21
	v_lshlrev_b32_e32 v24, 16, v40
	v_and_b32_e32 v40, 0xffff0000, v40
	v_mul_f32_e32 v39, v39, v39
	v_fmac_f32_e32 v38, v22, v22
	v_add_f32_e32 v36, v36, v37
	v_lshlrev_b32_e32 v25, 16, v41
	v_and_b32_e32 v41, 0xffff0000, v41
	v_mul_f32_e32 v40, v40, v40
	v_fmac_f32_e32 v39, v23, v23
	v_add_f32_e32 v36, v38, v36
	v_lshlrev_b32_e32 v26, 16, v42
	v_and_b32_e32 v42, 0xffff0000, v42
	v_mul_f32_e32 v41, v41, v41
	v_fmac_f32_e32 v40, v24, v24
	v_add_f32_e32 v36, v39, v36
	v_lshlrev_b32_e32 v27, 16, v43
	v_and_b32_e32 v43, 0xffff0000, v43
	v_mul_f32_e32 v42, v42, v42
	v_fmac_f32_e32 v41, v25, v25
	v_add_f32_e32 v36, v40, v36
	v_mul_f32_e32 v43, v43, v43
	v_fmac_f32_e32 v42, v26, v26
	v_add_f32_e32 v36, v41, v36
	v_add_f32_e32 v36, v42, v36
	v_fmac_f32_e32 v43, v27, v27
	v_add_f32_e32 v36, v43, v36
	ds_bpermute_b32 v37, v6, v36
	s_waitcnt lgkmcnt(0)
	v_add_f32_e32 v36, v36, v37
	ds_bpermute_b32 v37, v7, v36
	s_waitcnt lgkmcnt(0)
	v_add_f32_e32 v36, v36, v37
	ds_bpermute_b32 v37, v8, v36
	s_waitcnt lgkmcnt(0)
	v_add_f32_e32 v36, v36, v37
	ds_bpermute_b32 v37, v9, v36
	s_waitcnt lgkmcnt(0)
	v_add_f32_e32 v36, v36, v37
	ds_bpermute_b32 v37, v10, v36
	s_waitcnt lgkmcnt(0)
	v_add_f32_e32 v36, v36, v37
	ds_bpermute_b32 v37, v11, v36
	s_and_saveexec_b64 s[46:47], vcc
	s_cbranch_execz .LBB0_30
	s_waitcnt lgkmcnt(0)
	v_add_f32_e32 v36, v36, v37
	v_fmamk_f32 v36, v36, 0x3a800000, v162
	s_mov_b32 s0, 0x800000
	v_mul_f32_e32 v37, 0x4b800000, v36
	v_cmp_gt_f32_e64 s[0:1], s0, v36
	s_nop 1
	v_cndmask_b32_e64 v36, v36, v37, s[0:1]
	v_rsq_f32_e32 v36, v36
	s_nop 0
	v_mul_f32_e32 v37, 0x45800000, v36
	v_cndmask_b32_e64 v36, v36, v37, s[0:1]
	global_store_dword v[2:3], v36, off
	s_branch .LBB0_30
